# P8 final output stores without the nt hint (write-back through L2)
# speedup vs baseline: 1.0090x; 1.0090x over previous
.LBB0_1058:
	v_lshl_add_u32 v144, s35, 8, v133
	s_lshl_b32 s14, s36, 8
	s_ashr_i32 s15, s14, 31
	v_ashrrev_i32_e32 v145, 31, v144
	v_mov_b32_e32 v143, s15
	v_or_b32_e32 v142, s14, v132
	v_lshlrev_b64 v[150:151], 10, v[144:145]
	v_lshl_add_u64 v[150:151], v[150:151], 0, v[142:143]
	v_lshlrev_b64 v[152:153], 1, v[150:151]
	v_lshl_add_u64 v[154:155], s[82:83], 0, v[152:153]
	global_load_dwordx2 v[154:155], v[154:155], off
	v_lshl_add_u64 v[150:151], v[150:151], 2, s[74:75]
	v_or_b32_e32 v156, 32, v152
	v_mov_b32_e32 v157, v153
	v_lshl_add_u64 v[156:157], s[82:83], 0, v[156:157]
	s_and_b64 vcc, exec, s[0:1]
	s_mov_b64 s[0:1], -1
	s_waitcnt vmcnt(0)
	v_lshlrev_b32_e32 v158, 16, v154
	v_and_b32_e32 v159, 0xffff0000, v154
	v_lshlrev_b32_e32 v154, 16, v155
	v_and_b32_e32 v155, 0xffff0000, v155
	v_pk_add_f32 v[126:127], v[126:127], v[154:155]
	v_pk_add_f32 v[124:125], v[124:125], v[158:159]
	global_store_dwordx4 v[150:151], v[124:127], off
	global_load_dwordx2 v[124:125], v[156:157], off
	s_waitcnt vmcnt(0)
	v_lshlrev_b32_e32 v154, 16, v124
	v_and_b32_e32 v155, 0xffff0000, v124
	v_lshlrev_b32_e32 v124, 16, v125
	v_and_b32_e32 v125, 0xffff0000, v125
	v_or_b32_e32 v126, 0x100, v152
	v_mov_b32_e32 v127, v153
	v_pk_add_f32 v[122:123], v[122:123], v[124:125]
	v_pk_add_f32 v[120:121], v[120:121], v[154:155]
	v_lshl_add_u64 v[126:127], s[82:83], 0, v[126:127]
	global_store_dwordx4 v[150:151], v[120:123], off offset:64
	global_load_dwordx2 v[120:121], v[126:127], off
	v_or_b32_e32 v152, 0x120, v152
	v_lshl_add_u64 v[122:123], s[82:83], 0, v[152:153]
	s_waitcnt vmcnt(0)
	v_lshlrev_b32_e32 v124, 16, v120
	v_and_b32_e32 v125, 0xffff0000, v120
	v_lshlrev_b32_e32 v120, 16, v121
	v_and_b32_e32 v121, 0xffff0000, v121
	v_pk_add_f32 v[118:119], v[118:119], v[120:121]
	v_pk_add_f32 v[116:117], v[116:117], v[124:125]
	global_store_dwordx4 v[150:151], v[116:119], off offset:512
	global_load_dwordx2 v[116:117], v[122:123], off
	s_waitcnt vmcnt(0)
	v_lshlrev_b32_e32 v124, 16, v116
	v_or_b32_e32 v118, 16, v144
	v_ashrrev_i32_e32 v119, 31, v118
	v_lshlrev_b64 v[118:119], 10, v[118:119]
	v_lshl_add_u64 v[118:119], v[118:119], 0, v[142:143]
	v_and_b32_e32 v125, 0xffff0000, v116
	v_lshlrev_b32_e32 v116, 16, v117
	v_and_b32_e32 v117, 0xffff0000, v117
	v_lshlrev_b64 v[120:121], 1, v[118:119]
	v_pk_add_f32 v[114:115], v[114:115], v[116:117]
	v_pk_add_f32 v[112:113], v[112:113], v[124:125]
	v_lshl_add_u64 v[122:123], s[82:83], 0, v[120:121]
	global_store_dwordx4 v[150:151], v[112:115], off offset:576
	global_load_dwordx2 v[112:113], v[122:123], off
	v_or_b32_e32 v116, 32, v120
	v_lshl_add_u64 v[114:115], v[118:119], 2, s[74:75]
	v_mov_b32_e32 v117, v121
	v_lshl_add_u64 v[116:117], s[82:83], 0, v[116:117]
	s_waitcnt vmcnt(0)
	v_lshlrev_b32_e32 v118, 16, v112
	v_and_b32_e32 v119, 0xffff0000, v112
	v_lshlrev_b32_e32 v112, 16, v113
	v_and_b32_e32 v113, 0xffff0000, v113
	v_pk_add_f32 v[110:111], v[110:111], v[112:113]
	v_pk_add_f32 v[108:109], v[108:109], v[118:119]
	global_store_dwordx4 v[114:115], v[108:111], off
	global_load_dwordx2 v[108:109], v[116:117], off
	s_waitcnt vmcnt(0)
	v_lshlrev_b32_e32 v112, 16, v108
	v_and_b32_e32 v113, 0xffff0000, v108
	v_lshlrev_b32_e32 v108, 16, v109
	v_and_b32_e32 v109, 0xffff0000, v109
	v_or_b32_e32 v110, 0x100, v120
	v_mov_b32_e32 v111, v121
	v_pk_add_f32 v[106:107], v[106:107], v[108:109]
	v_pk_add_f32 v[104:105], v[104:105], v[112:113]
	v_lshl_add_u64 v[110:111], s[82:83], 0, v[110:111]
	global_store_dwordx4 v[114:115], v[104:107], off offset:64
	global_load_dwordx2 v[104:105], v[110:111], off
	v_or_b32_e32 v120, 0x120, v120
	v_lshl_add_u64 v[106:107], s[82:83], 0, v[120:121]
	s_waitcnt vmcnt(0)
	v_lshlrev_b32_e32 v108, 16, v104
	v_and_b32_e32 v109, 0xffff0000, v104
	v_lshlrev_b32_e32 v104, 16, v105
	v_and_b32_e32 v105, 0xffff0000, v105
	v_pk_add_f32 v[102:103], v[102:103], v[104:105]
	v_pk_add_f32 v[100:101], v[100:101], v[108:109]
	global_store_dwordx4 v[114:115], v[100:103], off offset:512
	global_load_dwordx2 v[100:101], v[106:107], off
	s_waitcnt vmcnt(0)
	v_lshlrev_b32_e32 v108, 16, v100
	v_or_b32_e32 v102, 32, v144
	v_ashrrev_i32_e32 v103, 31, v102
	v_lshlrev_b64 v[102:103], 10, v[102:103]
	v_lshl_add_u64 v[102:103], v[102:103], 0, v[142:143]
	v_and_b32_e32 v109, 0xffff0000, v100
	v_lshlrev_b32_e32 v100, 16, v101
	v_and_b32_e32 v101, 0xffff0000, v101
	v_lshlrev_b64 v[104:105], 1, v[102:103]
	v_pk_add_f32 v[98:99], v[98:99], v[100:101]
	v_pk_add_f32 v[96:97], v[96:97], v[108:109]
	v_lshl_add_u64 v[106:107], s[82:83], 0, v[104:105]
	global_store_dwordx4 v[114:115], v[96:99], off offset:576
	global_load_dwordx2 v[96:97], v[106:107], off
	v_or_b32_e32 v100, 32, v104
	v_lshl_add_u64 v[98:99], v[102:103], 2, s[74:75]
	v_mov_b32_e32 v101, v105
	v_lshl_add_u64 v[100:101], s[82:83], 0, v[100:101]
	s_waitcnt vmcnt(0)
	v_lshlrev_b32_e32 v102, 16, v96
	v_and_b32_e32 v103, 0xffff0000, v96
	v_lshlrev_b32_e32 v96, 16, v97
	v_and_b32_e32 v97, 0xffff0000, v97
	v_pk_add_f32 v[94:95], v[94:95], v[96:97]
	v_pk_add_f32 v[92:93], v[92:93], v[102:103]
	global_store_dwordx4 v[98:99], v[92:95], off
	global_load_dwordx2 v[92:93], v[100:101], off
	s_waitcnt vmcnt(0)
	v_lshlrev_b32_e32 v96, 16, v92
	v_and_b32_e32 v97, 0xffff0000, v92
	v_lshlrev_b32_e32 v92, 16, v93
	v_and_b32_e32 v93, 0xffff0000, v93
	v_or_b32_e32 v94, 0x100, v104
	v_mov_b32_e32 v95, v105
	v_pk_add_f32 v[90:91], v[90:91], v[92:93]
	v_pk_add_f32 v[88:89], v[88:89], v[96:97]
	v_lshl_add_u64 v[94:95], s[82:83], 0, v[94:95]
	global_store_dwordx4 v[98:99], v[88:91], off offset:64
	global_load_dwordx2 v[88:89], v[94:95], off
	v_or_b32_e32 v104, 0x120, v104
	v_lshl_add_u64 v[90:91], s[82:83], 0, v[104:105]
	s_waitcnt vmcnt(0)
	v_lshlrev_b32_e32 v92, 16, v88
	v_and_b32_e32 v93, 0xffff0000, v88
	v_lshlrev_b32_e32 v88, 16, v89
	v_and_b32_e32 v89, 0xffff0000, v89
	v_pk_add_f32 v[86:87], v[86:87], v[88:89]
	v_pk_add_f32 v[84:85], v[84:85], v[92:93]
	global_store_dwordx4 v[98:99], v[84:87], off offset:512
	global_load_dwordx2 v[84:85], v[90:91], off
	s_waitcnt vmcnt(0)
	v_lshlrev_b32_e32 v92, 16, v84
	v_or_b32_e32 v86, 48, v144
	v_ashrrev_i32_e32 v87, 31, v86
	v_lshlrev_b64 v[86:87], 10, v[86:87]
	v_lshl_add_u64 v[86:87], v[86:87], 0, v[142:143]
	v_and_b32_e32 v93, 0xffff0000, v84
	v_lshlrev_b32_e32 v84, 16, v85
	v_and_b32_e32 v85, 0xffff0000, v85
	v_lshlrev_b64 v[88:89], 1, v[86:87]
	v_pk_add_f32 v[82:83], v[82:83], v[84:85]
	v_pk_add_f32 v[80:81], v[80:81], v[92:93]
	v_lshl_add_u64 v[90:91], s[82:83], 0, v[88:89]
	global_store_dwordx4 v[98:99], v[80:83], off offset:576
	global_load_dwordx2 v[80:81], v[90:91], off
	v_or_b32_e32 v84, 32, v88
	v_lshl_add_u64 v[82:83], v[86:87], 2, s[74:75]
	v_mov_b32_e32 v85, v89
	v_lshl_add_u64 v[84:85], s[82:83], 0, v[84:85]
	s_waitcnt vmcnt(0)
	v_lshlrev_b32_e32 v86, 16, v80
	v_and_b32_e32 v87, 0xffff0000, v80
	v_lshlrev_b32_e32 v80, 16, v81
	v_and_b32_e32 v81, 0xffff0000, v81
	v_pk_add_f32 v[78:79], v[78:79], v[80:81]
	v_pk_add_f32 v[76:77], v[76:77], v[86:87]
	global_store_dwordx4 v[82:83], v[76:79], off
	global_load_dwordx2 v[76:77], v[84:85], off
	s_waitcnt vmcnt(0)
	v_lshlrev_b32_e32 v80, 16, v76
	v_and_b32_e32 v81, 0xffff0000, v76
	v_lshlrev_b32_e32 v76, 16, v77
	v_and_b32_e32 v77, 0xffff0000, v77
	v_or_b32_e32 v78, 0x100, v88
	v_mov_b32_e32 v79, v89
	v_pk_add_f32 v[74:75], v[74:75], v[76:77]
	v_pk_add_f32 v[72:73], v[72:73], v[80:81]
	v_lshl_add_u64 v[78:79], s[82:83], 0, v[78:79]
	global_store_dwordx4 v[82:83], v[72:75], off offset:64
	global_load_dwordx2 v[72:73], v[78:79], off
	v_or_b32_e32 v88, 0x120, v88
	v_lshl_add_u64 v[74:75], s[82:83], 0, v[88:89]
	s_waitcnt vmcnt(0)
	v_lshlrev_b32_e32 v76, 16, v72
	v_and_b32_e32 v77, 0xffff0000, v72
	v_lshlrev_b32_e32 v72, 16, v73
	v_and_b32_e32 v73, 0xffff0000, v73
	v_pk_add_f32 v[70:71], v[70:71], v[72:73]
	v_pk_add_f32 v[68:69], v[68:69], v[76:77]
	global_store_dwordx4 v[82:83], v[68:71], off offset:512
	global_load_dwordx2 v[68:69], v[74:75], off
	s_waitcnt vmcnt(0)
	v_lshlrev_b32_e32 v76, 16, v68
	v_add_u32_e32 v70, 0x80, v144
	v_ashrrev_i32_e32 v71, 31, v70
	v_lshlrev_b64 v[70:71], 10, v[70:71]
	v_lshl_add_u64 v[70:71], v[70:71], 0, v[142:143]
	v_and_b32_e32 v77, 0xffff0000, v68
	v_lshlrev_b32_e32 v68, 16, v69
	v_and_b32_e32 v69, 0xffff0000, v69
	v_lshlrev_b64 v[72:73], 1, v[70:71]
	v_pk_add_f32 v[66:67], v[66:67], v[68:69]
	v_pk_add_f32 v[64:65], v[64:65], v[76:77]
	v_lshl_add_u64 v[74:75], s[82:83], 0, v[72:73]
	global_store_dwordx4 v[82:83], v[64:67], off offset:576
	global_load_dwordx2 v[64:65], v[74:75], off
	v_or_b32_e32 v68, 32, v72
	v_lshl_add_u64 v[66:67], v[70:71], 2, s[74:75]
	v_mov_b32_e32 v69, v73
	v_lshl_add_u64 v[68:69], s[82:83], 0, v[68:69]
	s_waitcnt vmcnt(0)
	v_lshlrev_b32_e32 v70, 16, v64
	v_and_b32_e32 v71, 0xffff0000, v64
	v_lshlrev_b32_e32 v64, 16, v65
	v_and_b32_e32 v65, 0xffff0000, v65
	v_pk_add_f32 v[62:63], v[62:63], v[64:65]
	v_pk_add_f32 v[60:61], v[60:61], v[70:71]
	global_store_dwordx4 v[66:67], v[60:63], off
	global_load_dwordx2 v[60:61], v[68:69], off
	s_waitcnt vmcnt(0)
	v_lshlrev_b32_e32 v64, 16, v60
	v_and_b32_e32 v65, 0xffff0000, v60
	v_lshlrev_b32_e32 v60, 16, v61
	v_and_b32_e32 v61, 0xffff0000, v61
	v_or_b32_e32 v62, 0x100, v72
	v_mov_b32_e32 v63, v73
	v_pk_add_f32 v[58:59], v[58:59], v[60:61]
	v_pk_add_f32 v[56:57], v[56:57], v[64:65]
	v_lshl_add_u64 v[62:63], s[82:83], 0, v[62:63]
	global_store_dwordx4 v[66:67], v[56:59], off offset:64
	global_load_dwordx2 v[56:57], v[62:63], off
	v_or_b32_e32 v72, 0x120, v72
	v_lshl_add_u64 v[58:59], s[82:83], 0, v[72:73]
	s_waitcnt vmcnt(0)
	v_lshlrev_b32_e32 v60, 16, v56
	v_and_b32_e32 v61, 0xffff0000, v56
	v_lshlrev_b32_e32 v56, 16, v57
	v_and_b32_e32 v57, 0xffff0000, v57
	v_pk_add_f32 v[54:55], v[54:55], v[56:57]
	v_pk_add_f32 v[52:53], v[52:53], v[60:61]
	global_store_dwordx4 v[66:67], v[52:55], off offset:512
	global_load_dwordx2 v[52:53], v[58:59], off
	s_waitcnt vmcnt(0)
	v_lshlrev_b32_e32 v60, 16, v52
	v_add_u32_e32 v54, 0x90, v144
	v_ashrrev_i32_e32 v55, 31, v54
	v_lshlrev_b64 v[54:55], 10, v[54:55]
	v_lshl_add_u64 v[54:55], v[54:55], 0, v[142:143]
	v_and_b32_e32 v61, 0xffff0000, v52
	v_lshlrev_b32_e32 v52, 16, v53
	v_and_b32_e32 v53, 0xffff0000, v53
	v_lshlrev_b64 v[56:57], 1, v[54:55]
	v_pk_add_f32 v[50:51], v[50:51], v[52:53]
	v_pk_add_f32 v[48:49], v[48:49], v[60:61]
	v_lshl_add_u64 v[58:59], s[82:83], 0, v[56:57]
	global_store_dwordx4 v[66:67], v[48:51], off offset:576
	global_load_dwordx2 v[48:49], v[58:59], off
	v_or_b32_e32 v52, 32, v56
	v_lshl_add_u64 v[50:51], v[54:55], 2, s[74:75]
	v_mov_b32_e32 v53, v57
	v_lshl_add_u64 v[52:53], s[82:83], 0, v[52:53]
	s_waitcnt vmcnt(0)
	v_lshlrev_b32_e32 v54, 16, v48
	v_and_b32_e32 v55, 0xffff0000, v48
	v_lshlrev_b32_e32 v48, 16, v49
	v_and_b32_e32 v49, 0xffff0000, v49
	v_pk_add_f32 v[46:47], v[46:47], v[48:49]
	v_pk_add_f32 v[44:45], v[44:45], v[54:55]
	global_store_dwordx4 v[50:51], v[44:47], off
	global_load_dwordx2 v[44:45], v[52:53], off
	s_waitcnt vmcnt(0)
	v_lshlrev_b32_e32 v48, 16, v44
	v_and_b32_e32 v49, 0xffff0000, v44
	v_lshlrev_b32_e32 v44, 16, v45
	v_and_b32_e32 v45, 0xffff0000, v45
	v_or_b32_e32 v46, 0x100, v56
	v_mov_b32_e32 v47, v57
	v_pk_add_f32 v[42:43], v[42:43], v[44:45]
	v_pk_add_f32 v[40:41], v[40:41], v[48:49]
	v_lshl_add_u64 v[46:47], s[82:83], 0, v[46:47]
	global_store_dwordx4 v[50:51], v[40:43], off offset:64
	global_load_dwordx2 v[40:41], v[46:47], off
	v_or_b32_e32 v56, 0x120, v56
	v_lshl_add_u64 v[42:43], s[82:83], 0, v[56:57]
	s_waitcnt vmcnt(0)
	v_lshlrev_b32_e32 v44, 16, v40
	v_and_b32_e32 v45, 0xffff0000, v40
	v_lshlrev_b32_e32 v40, 16, v41
	v_and_b32_e32 v41, 0xffff0000, v41
	v_pk_add_f32 v[38:39], v[38:39], v[40:41]
	v_pk_add_f32 v[36:37], v[36:37], v[44:45]
	global_store_dwordx4 v[50:51], v[36:39], off offset:512
	global_load_dwordx2 v[36:37], v[42:43], off
	s_waitcnt vmcnt(0)
	v_lshlrev_b32_e32 v44, 16, v36
	v_add_u32_e32 v38, 0xa0, v144
	v_ashrrev_i32_e32 v39, 31, v38
	v_lshlrev_b64 v[38:39], 10, v[38:39]
	v_lshl_add_u64 v[38:39], v[38:39], 0, v[142:143]
	v_and_b32_e32 v45, 0xffff0000, v36
	v_lshlrev_b32_e32 v36, 16, v37
	v_and_b32_e32 v37, 0xffff0000, v37
	v_lshlrev_b64 v[40:41], 1, v[38:39]
	v_pk_add_f32 v[34:35], v[34:35], v[36:37]
	v_pk_add_f32 v[32:33], v[32:33], v[44:45]
	v_lshl_add_u64 v[42:43], s[82:83], 0, v[40:41]
	global_store_dwordx4 v[50:51], v[32:35], off offset:576
	global_load_dwordx2 v[32:33], v[42:43], off
	v_or_b32_e32 v36, 32, v40
	v_lshl_add_u64 v[34:35], v[38:39], 2, s[74:75]
	v_mov_b32_e32 v37, v41
	v_lshl_add_u64 v[36:37], s[82:83], 0, v[36:37]
	s_waitcnt vmcnt(0)
	v_lshlrev_b32_e32 v38, 16, v32
	v_and_b32_e32 v39, 0xffff0000, v32
	v_lshlrev_b32_e32 v32, 16, v33
	v_and_b32_e32 v33, 0xffff0000, v33
	v_pk_add_f32 v[30:31], v[30:31], v[32:33]
	v_pk_add_f32 v[28:29], v[28:29], v[38:39]
	global_store_dwordx4 v[34:35], v[28:31], off
	global_load_dwordx2 v[28:29], v[36:37], off
	s_waitcnt vmcnt(0)
	v_lshlrev_b32_e32 v32, 16, v28
	v_and_b32_e32 v33, 0xffff0000, v28
	v_lshlrev_b32_e32 v28, 16, v29
	v_and_b32_e32 v29, 0xffff0000, v29
	v_or_b32_e32 v30, 0x100, v40
	v_mov_b32_e32 v31, v41
	v_pk_add_f32 v[26:27], v[26:27], v[28:29]
	v_pk_add_f32 v[24:25], v[24:25], v[32:33]
	v_lshl_add_u64 v[30:31], s[82:83], 0, v[30:31]
	global_store_dwordx4 v[34:35], v[24:27], off offset:64
	global_load_dwordx2 v[24:25], v[30:31], off
	v_or_b32_e32 v40, 0x120, v40
	v_lshl_add_u64 v[26:27], s[82:83], 0, v[40:41]
	s_waitcnt vmcnt(0)
	v_lshlrev_b32_e32 v28, 16, v24
	v_and_b32_e32 v29, 0xffff0000, v24
	v_lshlrev_b32_e32 v24, 16, v25
	v_and_b32_e32 v25, 0xffff0000, v25
	v_pk_add_f32 v[22:23], v[22:23], v[24:25]
	v_pk_add_f32 v[20:21], v[20:21], v[28:29]
	global_store_dwordx4 v[34:35], v[20:23], off offset:512
	global_load_dwordx2 v[20:21], v[26:27], off
	s_waitcnt vmcnt(0)
	v_lshlrev_b32_e32 v28, 16, v20
	v_add_u32_e32 v22, 0xb0, v144
	v_ashrrev_i32_e32 v23, 31, v22
	v_lshlrev_b64 v[22:23], 10, v[22:23]
	v_lshl_add_u64 v[22:23], v[22:23], 0, v[142:143]
	v_and_b32_e32 v29, 0xffff0000, v20
	v_lshlrev_b32_e32 v20, 16, v21
	v_and_b32_e32 v21, 0xffff0000, v21
	v_lshlrev_b64 v[24:25], 1, v[22:23]
	v_pk_add_f32 v[18:19], v[18:19], v[20:21]
	v_pk_add_f32 v[16:17], v[16:17], v[28:29]
	v_lshl_add_u64 v[26:27], s[82:83], 0, v[24:25]
	global_store_dwordx4 v[34:35], v[16:19], off offset:576
	global_load_dwordx2 v[16:17], v[26:27], off
	v_or_b32_e32 v20, 32, v24
	v_lshl_add_u64 v[18:19], v[22:23], 2, s[74:75]
	v_mov_b32_e32 v21, v25
	v_lshl_add_u64 v[20:21], s[82:83], 0, v[20:21]
	s_waitcnt vmcnt(0)
	v_lshlrev_b32_e32 v22, 16, v16
	v_and_b32_e32 v23, 0xffff0000, v16
	v_lshlrev_b32_e32 v16, 16, v17
	v_and_b32_e32 v17, 0xffff0000, v17
	v_pk_add_f32 v[14:15], v[14:15], v[16:17]
	v_pk_add_f32 v[12:13], v[12:13], v[22:23]
	global_store_dwordx4 v[18:19], v[12:15], off
	global_load_dwordx2 v[12:13], v[20:21], off
	s_waitcnt vmcnt(0)
	v_lshlrev_b32_e32 v16, 16, v12
	v_and_b32_e32 v17, 0xffff0000, v12
	v_lshlrev_b32_e32 v12, 16, v13
	v_and_b32_e32 v13, 0xffff0000, v13
	v_or_b32_e32 v14, 0x100, v24
	v_mov_b32_e32 v15, v25
	v_pk_add_f32 v[10:11], v[10:11], v[12:13]
	v_pk_add_f32 v[8:9], v[8:9], v[16:17]
	v_lshl_add_u64 v[14:15], s[82:83], 0, v[14:15]
	global_store_dwordx4 v[18:19], v[8:11], off offset:64
	global_load_dwordx2 v[8:9], v[14:15], off
	v_or_b32_e32 v24, 0x120, v24
	v_lshl_add_u64 v[10:11], s[82:83], 0, v[24:25]
	s_waitcnt vmcnt(0)
	v_lshlrev_b32_e32 v12, 16, v8
	v_and_b32_e32 v13, 0xffff0000, v8
	v_lshlrev_b32_e32 v8, 16, v9
	v_and_b32_e32 v9, 0xffff0000, v9
	v_pk_add_f32 v[6:7], v[6:7], v[8:9]
	v_pk_add_f32 v[4:5], v[4:5], v[12:13]
	global_store_dwordx4 v[18:19], v[4:7], off offset:512
	global_load_dwordx2 v[4:5], v[10:11], off
	s_waitcnt vmcnt(0)
	v_lshlrev_b32_e32 v6, 16, v4
	v_and_b32_e32 v7, 0xffff0000, v4
	v_lshlrev_b32_e32 v4, 16, v5
	v_and_b32_e32 v5, 0xffff0000, v5
	v_pk_add_f32 v[2:3], v[2:3], v[4:5]
	v_pk_add_f32 v[0:1], v[0:1], v[6:7]
	global_store_dwordx4 v[18:19], v[0:3], off offset:576
	s_cbranch_vccnz .LBB0_1043
	s_andn2_b64 vcc, exec, s[6:7]
	s_cbranch_vccnz .LBB0_1042
	s_barrier
	s_branch .LBB0_1042
